# P8 epilogue: residual loads of the tile's second half issued together with the first half's loads (free registers) instead of after the first half's stores and a full wait
# speedup vs baseline: 1.0057x; 1.0006x over previous
.LBB0_1092:
	v_lshl_or_b32 v128, s47, 8, v166
	v_lshl_add_u32 v160, s46, 8, v164
	s_ashr_i32 s20, s46, 3
	v_ashrrev_i32_e32 v129, 31, v128
	v_ashrrev_i32_e32 v161, 31, v160
	s_mul_hi_i32 s21, s20, 0xc000
	s_mul_i32 s20, s20, 0xc000
	v_lshl_add_u64 v[158:159], v[128:129], 1, s[28:29]
	v_lshlrev_b64 v[130:131], 12, v[160:161]
	s_add_u32 s20, s35, s20
	v_lshl_add_u64 v[130:131], v[158:159], 0, v[130:131]
	v_lshlrev_b64 v[156:157], 2, v[128:129]
	s_addc_u32 s21, s44, s21
	global_load_dwordx2 v[170:171], v[130:131], off nt
	global_load_dwordx2 v[172:173], v[130:131], off offset:32 nt
	global_load_dwordx2 v[176:177], v[130:131], off offset:288 nt
	v_lshl_add_u64 v[128:129], s[20:21], 0, v[156:157]
	v_or_b32_e32 v178, 16, v160
	global_load_dwordx2 v[174:175], v[130:131], off offset:256 nt
	global_load_dwordx4 v[132:135], v[128:129], off offset:512
	global_load_dwordx4 v[140:143], v[128:129], off
	global_load_dwordx4 v[136:139], v[128:129], off offset:64
	v_ashrrev_i32_e32 v179, 31, v178
	global_load_dwordx4 v[128:131], v[128:129], off offset:576
	v_lshlrev_b64 v[162:163], 12, v[178:179]
	v_lshl_add_u64 v[162:163], v[158:159], 0, v[162:163]
	global_load_dwordx2 v[180:181], v[162:163], off nt
	global_load_dwordx2 v[182:183], v[162:163], off offset:32 nt
	global_load_dwordx2 v[184:185], v[162:163], off offset:256 nt
	global_load_dwordx2 v[186:187], v[162:163], off offset:288 nt
	v_or_b32_e32 v188, 32, v160
	v_ashrrev_i32_e32 v189, 31, v188
	v_lshlrev_b64 v[162:163], 12, v[188:189]
	v_lshl_add_u64 v[190:191], v[158:159], 0, v[162:163]
	global_load_dwordx2 v[192:193], v[190:191], off nt
	global_load_dwordx2 v[196:197], v[190:191], off offset:32 nt
	v_or_b32_e32 v162, 48, v160
	v_ashrrev_i32_e32 v163, 31, v162
	v_lshlrev_b64 v[198:199], 12, v[162:163]
	v_lshl_add_u64 v[198:199], v[158:159], 0, v[198:199]
	global_load_dwordx2 v[200:201], v[190:191], off offset:256 nt
	s_nop 0
	global_load_dwordx2 v[190:191], v[190:191], off offset:288 nt
	s_nop 0
	global_load_dwordx2 v[202:203], v[198:199], off nt
	global_load_dwordx2 v[204:205], v[198:199], off offset:32 nt
	global_load_dwordx2 v[206:207], v[198:199], off offset:256 nt
	s_nop 0
	global_load_dwordx2 v[198:199], v[198:199], off offset:288 nt
	v_lshlrev_b64 v[194:195], 13, v[160:161]
	v_lshl_add_u64 v[194:195], s[6:7], 0, v[194:195]
	v_lshlrev_b64 v[178:179], 13, v[178:179]
	v_lshl_add_u64 v[194:195], v[194:195], 0, v[156:157]
	v_lshl_add_u64 v[178:179], s[6:7], 0, v[178:179]
	v_lshl_add_u64 v[178:179], v[178:179], 0, v[156:157]
	s_and_b64 vcc, exec, s[0:1]
	s_mov_b64 s[0:1], -1
	v_add_u32_e32 v208, 0x80, v160
	v_ashrrev_i32_e32 v209, 31, v208
	v_lshlrev_b64 v[208:209], 12, v[208:209]
	v_lshl_add_u64 v[208:209], v[158:159], 0, v[208:209]
	global_load_dwordx2 v[220:221], v[208:209], off nt
	global_load_dwordx2 v[222:223], v[208:209], off offset:32 nt
	global_load_dwordx2 v[224:225], v[208:209], off offset:256 nt
	global_load_dwordx2 v[226:227], v[208:209], off offset:288 nt
	v_add_u32_e32 v208, 0x90, v160
	v_ashrrev_i32_e32 v209, 31, v208
	v_lshlrev_b64 v[208:209], 12, v[208:209]
	v_lshl_add_u64 v[208:209], v[158:159], 0, v[208:209]
	global_load_dwordx2 v[228:229], v[208:209], off nt
	global_load_dwordx2 v[230:231], v[208:209], off offset:32 nt
	global_load_dwordx2 v[232:233], v[208:209], off offset:256 nt
	global_load_dwordx2 v[234:235], v[208:209], off offset:288 nt
	v_add_u32_e32 v208, 0xa0, v160
	v_ashrrev_i32_e32 v209, 31, v208
	v_lshlrev_b64 v[208:209], 12, v[208:209]
	v_lshl_add_u64 v[208:209], v[158:159], 0, v[208:209]
	global_load_dwordx2 v[236:237], v[208:209], off nt
	global_load_dwordx2 v[238:239], v[208:209], off offset:32 nt
	global_load_dwordx2 v[240:241], v[208:209], off offset:256 nt
	global_load_dwordx2 v[242:243], v[208:209], off offset:288 nt
	v_add_u32_e32 v208, 0xb0, v160
	v_ashrrev_i32_e32 v209, 31, v208
	v_lshlrev_b64 v[208:209], 12, v[208:209]
	v_lshl_add_u64 v[208:209], v[158:159], 0, v[208:209]
	global_load_dwordx2 v[244:245], v[208:209], off nt
	global_load_dwordx2 v[246:247], v[208:209], off offset:32 nt
	global_load_dwordx2 v[248:249], v[208:209], off offset:256 nt
	global_load_dwordx2 v[250:251], v[208:209], off offset:288 nt
	s_waitcnt vmcnt(0)
	v_lshlrev_b32_e32 v208, 16, v170
	v_and_b32_e32 v209, 0xffff0000, v170
	v_lshlrev_b32_e32 v170, 16, v171
	v_and_b32_e32 v171, 0xffff0000, v171
	v_lshlrev_b32_e32 v210, 16, v172
	v_and_b32_e32 v211, 0xffff0000, v172
	v_lshlrev_b32_e32 v172, 16, v173
	v_and_b32_e32 v173, 0xffff0000, v173
	v_lshlrev_b32_e32 v214, 16, v176
	v_and_b32_e32 v215, 0xffff0000, v176
	v_lshlrev_b32_e32 v176, 16, v177
	v_and_b32_e32 v177, 0xffff0000, v177
	v_lshlrev_b32_e32 v212, 16, v174
	v_and_b32_e32 v213, 0xffff0000, v174
	v_lshlrev_b32_e32 v174, 16, v175
	v_and_b32_e32 v175, 0xffff0000, v175
	v_pk_fma_f32 v[126:127], v[126:127], v[142:143], v[170:171]
	v_pk_fma_f32 v[124:125], v[124:125], v[140:141], v[208:209]
	v_pk_fma_f32 v[122:123], v[122:123], v[138:139], v[172:173]
	v_pk_fma_f32 v[110:111], v[110:111], v[130:131], v[176:177]
	v_pk_fma_f32 v[108:109], v[108:109], v[128:129], v[214:215]
	v_lshlrev_b32_e32 v170, 16, v180
	v_and_b32_e32 v171, 0xffff0000, v180
	v_lshlrev_b32_e32 v172, 16, v181
	v_and_b32_e32 v173, 0xffff0000, v181
	v_pk_fma_f32 v[120:121], v[120:121], v[136:137], v[210:211]
	v_pk_fma_f32 v[114:115], v[114:115], v[134:135], v[174:175]
	v_pk_fma_f32 v[112:113], v[112:113], v[132:133], v[212:213]
	flat_store_dwordx4 v[194:195], v[124:127] nt
	flat_store_dwordx4 v[194:195], v[120:123] offset:64 nt
	flat_store_dwordx4 v[194:195], v[112:115] offset:512 nt
	flat_store_dwordx4 v[194:195], v[108:111] offset:576 nt
	v_lshlrev_b32_e32 v174, 16, v182
	v_and_b32_e32 v175, 0xffff0000, v182
	v_pk_fma_f32 v[110:111], v[118:119], v[142:143], v[172:173]
	v_pk_fma_f32 v[108:109], v[116:117], v[140:141], v[170:171]
	flat_store_dwordx4 v[178:179], v[108:111] nt
	v_pk_fma_f32 v[104:105], v[104:105], v[136:137], v[174:175]
	s_nop 0
	v_lshlrev_b32_e32 v108, 16, v183
	v_and_b32_e32 v109, 0xffff0000, v183
	v_pk_fma_f32 v[106:107], v[106:107], v[138:139], v[108:109]
	flat_store_dwordx4 v[178:179], v[104:107] offset:64 nt
	s_nop 1
	v_lshlrev_b32_e32 v104, 16, v184
	v_and_b32_e32 v105, 0xffff0000, v184
	v_lshlrev_b32_e32 v106, 16, v185
	v_and_b32_e32 v107, 0xffff0000, v185
	v_pk_fma_f32 v[102:103], v[102:103], v[134:135], v[106:107]
	v_pk_fma_f32 v[100:101], v[100:101], v[132:133], v[104:105]
	flat_store_dwordx4 v[178:179], v[100:103] offset:512 nt
	s_nop 1
	v_lshlrev_b32_e32 v100, 16, v186
	v_and_b32_e32 v101, 0xffff0000, v186
	v_lshlrev_b32_e32 v102, 16, v187
	v_and_b32_e32 v103, 0xffff0000, v187
	v_pk_fma_f32 v[94:95], v[94:95], v[130:131], v[102:103]
	v_pk_fma_f32 v[92:93], v[92:93], v[128:129], v[100:101]
	flat_store_dwordx4 v[178:179], v[92:95] offset:576 nt
	s_nop 1
	v_lshlrev_b32_e32 v92, 16, v192
	v_and_b32_e32 v93, 0xffff0000, v192
	v_pk_fma_f32 v[92:93], v[96:97], v[140:141], v[92:93]
	v_lshlrev_b64 v[96:97], 13, v[188:189]
	v_lshlrev_b32_e32 v94, 16, v193
	v_and_b32_e32 v95, 0xffff0000, v193
	v_lshl_add_u64 v[96:97], s[6:7], 0, v[96:97]
	v_pk_fma_f32 v[94:95], v[98:99], v[142:143], v[94:95]
	v_lshl_add_u64 v[96:97], v[96:97], 0, v[156:157]
	flat_store_dwordx4 v[96:97], v[92:95] nt
	v_add_u32_e32 v98, 0xb0, v160
	v_ashrrev_i32_e32 v99, 31, v98
	v_lshlrev_b32_e32 v92, 16, v196
	v_and_b32_e32 v93, 0xffff0000, v196
	v_lshlrev_b32_e32 v94, 16, v197
	v_and_b32_e32 v95, 0xffff0000, v197
	v_pk_fma_f32 v[90:91], v[90:91], v[138:139], v[94:95]
	v_pk_fma_f32 v[88:89], v[88:89], v[136:137], v[92:93]
	flat_store_dwordx4 v[96:97], v[88:91] offset:64 nt
	s_nop 1
	v_lshlrev_b32_e32 v88, 16, v200
	v_and_b32_e32 v89, 0xffff0000, v200
	v_lshlrev_b32_e32 v90, 16, v201
	v_and_b32_e32 v91, 0xffff0000, v201
	v_pk_fma_f32 v[86:87], v[86:87], v[134:135], v[90:91]
	v_pk_fma_f32 v[84:85], v[84:85], v[132:133], v[88:89]
	flat_store_dwordx4 v[96:97], v[84:87] offset:512 nt
	v_add_u32_e32 v88, 0xa0, v160
	v_ashrrev_i32_e32 v89, 31, v88
	v_lshlrev_b32_e32 v84, 16, v190
	v_and_b32_e32 v85, 0xffff0000, v190
	v_lshlrev_b32_e32 v86, 16, v191
	v_and_b32_e32 v87, 0xffff0000, v191
	v_pk_fma_f32 v[78:79], v[78:79], v[130:131], v[86:87]
	v_pk_fma_f32 v[76:77], v[76:77], v[128:129], v[84:85]
	flat_store_dwordx4 v[96:97], v[76:79] offset:576 nt
	s_nop 1
	v_lshlrev_b32_e32 v76, 16, v202
	v_and_b32_e32 v77, 0xffff0000, v202
	v_pk_fma_f32 v[76:77], v[80:81], v[140:141], v[76:77]
	v_lshlrev_b64 v[80:81], 13, v[162:163]
	v_lshlrev_b32_e32 v78, 16, v203
	v_and_b32_e32 v79, 0xffff0000, v203
	v_lshl_add_u64 v[80:81], s[6:7], 0, v[80:81]
	v_pk_fma_f32 v[78:79], v[82:83], v[142:143], v[78:79]
	v_lshl_add_u64 v[80:81], v[80:81], 0, v[156:157]
	flat_store_dwordx4 v[80:81], v[76:79] nt
	s_nop 1
	v_lshlrev_b32_e32 v76, 16, v204
	v_and_b32_e32 v77, 0xffff0000, v204
	v_lshlrev_b32_e32 v78, 16, v205
	v_and_b32_e32 v79, 0xffff0000, v205
	v_pk_fma_f32 v[74:75], v[74:75], v[138:139], v[78:79]
	v_pk_fma_f32 v[72:73], v[72:73], v[136:137], v[76:77]
	flat_store_dwordx4 v[80:81], v[72:75] offset:64 nt
	v_add_u32_e32 v78, 0x90, v160
	v_ashrrev_i32_e32 v79, 31, v78
	v_lshlrev_b32_e32 v72, 16, v206
	v_and_b32_e32 v73, 0xffff0000, v206
	v_lshlrev_b32_e32 v74, 16, v207
	v_and_b32_e32 v75, 0xffff0000, v207
	v_pk_fma_f32 v[70:71], v[70:71], v[134:135], v[74:75]
	v_pk_fma_f32 v[68:69], v[68:69], v[132:133], v[72:73]
	flat_store_dwordx4 v[80:81], v[68:71] offset:512 nt
	s_nop 1
	v_lshlrev_b32_e32 v68, 16, v198
	v_and_b32_e32 v69, 0xffff0000, v198
	v_lshlrev_b32_e32 v70, 16, v199
	v_and_b32_e32 v71, 0xffff0000, v199
	v_pk_fma_f32 v[64:65], v[64:65], v[128:129], v[68:69]
	v_add_u32_e32 v68, 0x80, v160
	v_pk_fma_f32 v[66:67], v[66:67], v[130:131], v[70:71]
	v_ashrrev_i32_e32 v69, 31, v68
	flat_store_dwordx4 v[80:81], v[64:67] offset:576 nt
	s_nop 1
	v_lshlrev_b64 v[64:65], 12, v[68:69]
	v_lshl_add_u64 v[64:65], v[158:159], 0, v[64:65]
	v_mov_b64_e32 v[70:71], v[220:221]
	v_mov_b64_e32 v[72:73], v[222:223]
	v_mov_b64_e32 v[74:75], v[224:225]
	v_mov_b64_e32 v[76:77], v[226:227]
	v_lshlrev_b64 v[64:65], 12, v[78:79]
	v_lshl_add_u64 v[64:65], v[158:159], 0, v[64:65]
	v_mov_b64_e32 v[80:81], v[228:229]
	v_mov_b64_e32 v[82:83], v[230:231]
	v_mov_b64_e32 v[84:85], v[232:233]
	v_mov_b64_e32 v[86:87], v[234:235]
	v_lshlrev_b64 v[64:65], 12, v[88:89]
	v_lshl_add_u64 v[64:65], v[158:159], 0, v[64:65]
	v_mov_b64_e32 v[90:91], v[236:237]
	v_mov_b64_e32 v[92:93], v[238:239]
	v_mov_b64_e32 v[94:95], v[240:241]
	v_mov_b64_e32 v[96:97], v[242:243]
	v_lshlrev_b64 v[64:65], 12, v[98:99]
	v_lshl_add_u64 v[64:65], v[158:159], 0, v[64:65]
	v_mov_b64_e32 v[100:101], v[244:245]
	v_mov_b64_e32 v[102:103], v[246:247]
	v_mov_b64_e32 v[66:67], v[248:249]
	s_nop 0
	v_mov_b64_e32 v[64:65], v[250:251]
	v_lshlrev_b64 v[68:69], 13, v[68:69]
	v_lshl_add_u64 v[68:69], s[6:7], 0, v[68:69]
	v_lshl_add_u64 v[68:69], v[68:69], 0, v[156:157]
	s_nop 0
	v_lshlrev_b32_e32 v104, 16, v70
	v_and_b32_e32 v105, 0xffff0000, v70
	v_lshlrev_b32_e32 v70, 16, v71
	v_and_b32_e32 v71, 0xffff0000, v71
	v_pk_fma_f32 v[62:63], v[62:63], v[142:143], v[70:71]
	v_pk_fma_f32 v[60:61], v[60:61], v[140:141], v[104:105]
	flat_store_dwordx4 v[68:69], v[60:63] nt
	s_nop 1
	v_lshlrev_b32_e32 v60, 16, v72
	v_and_b32_e32 v61, 0xffff0000, v72
	v_lshlrev_b32_e32 v62, 16, v73
	v_and_b32_e32 v63, 0xffff0000, v73
	v_pk_fma_f32 v[58:59], v[58:59], v[138:139], v[62:63]
	v_pk_fma_f32 v[56:57], v[56:57], v[136:137], v[60:61]
	flat_store_dwordx4 v[68:69], v[56:59] offset:64 nt
	s_nop 1
	v_lshlrev_b32_e32 v56, 16, v74
	v_and_b32_e32 v57, 0xffff0000, v74
	v_lshlrev_b32_e32 v58, 16, v75
	v_and_b32_e32 v59, 0xffff0000, v75
	v_pk_fma_f32 v[54:55], v[54:55], v[134:135], v[58:59]
	v_pk_fma_f32 v[52:53], v[52:53], v[132:133], v[56:57]
	flat_store_dwordx4 v[68:69], v[52:55] offset:512 nt
	s_nop 1
	v_lshlrev_b32_e32 v52, 16, v76
	v_and_b32_e32 v53, 0xffff0000, v76
	v_lshlrev_b32_e32 v54, 16, v77
	v_and_b32_e32 v55, 0xffff0000, v77
	v_pk_fma_f32 v[46:47], v[46:47], v[130:131], v[54:55]
	v_pk_fma_f32 v[44:45], v[44:45], v[128:129], v[52:53]
	flat_store_dwordx4 v[68:69], v[44:47] offset:576 nt
	s_nop 1
	v_lshlrev_b32_e32 v44, 16, v80
	v_and_b32_e32 v45, 0xffff0000, v80
	v_pk_fma_f32 v[44:45], v[48:49], v[140:141], v[44:45]
	v_lshlrev_b64 v[48:49], 13, v[78:79]
	v_lshlrev_b32_e32 v46, 16, v81
	v_and_b32_e32 v47, 0xffff0000, v81
	v_lshl_add_u64 v[48:49], s[6:7], 0, v[48:49]
	v_pk_fma_f32 v[46:47], v[50:51], v[142:143], v[46:47]
	v_lshl_add_u64 v[48:49], v[48:49], 0, v[156:157]
	flat_store_dwordx4 v[48:49], v[44:47] nt
	s_nop 1
	v_lshlrev_b32_e32 v44, 16, v82
	v_and_b32_e32 v45, 0xffff0000, v82
	v_lshlrev_b32_e32 v46, 16, v83
	v_and_b32_e32 v47, 0xffff0000, v83
	v_pk_fma_f32 v[42:43], v[42:43], v[138:139], v[46:47]
	v_pk_fma_f32 v[40:41], v[40:41], v[136:137], v[44:45]
	flat_store_dwordx4 v[48:49], v[40:43] offset:64 nt
	s_nop 1
	v_lshlrev_b32_e32 v40, 16, v84
	v_and_b32_e32 v41, 0xffff0000, v84
	v_lshlrev_b32_e32 v42, 16, v85
	v_and_b32_e32 v43, 0xffff0000, v85
	v_pk_fma_f32 v[38:39], v[38:39], v[134:135], v[42:43]
	v_pk_fma_f32 v[36:37], v[36:37], v[132:133], v[40:41]
	flat_store_dwordx4 v[48:49], v[36:39] offset:512 nt
	s_nop 1
	v_lshlrev_b32_e32 v36, 16, v86
	v_and_b32_e32 v37, 0xffff0000, v86
	v_lshlrev_b32_e32 v38, 16, v87
	v_and_b32_e32 v39, 0xffff0000, v87
	v_pk_fma_f32 v[30:31], v[30:31], v[130:131], v[38:39]
	v_pk_fma_f32 v[28:29], v[28:29], v[128:129], v[36:37]
	flat_store_dwordx4 v[48:49], v[28:31] offset:576 nt
	s_nop 1
	v_lshlrev_b32_e32 v28, 16, v90
	v_and_b32_e32 v29, 0xffff0000, v90
	v_pk_fma_f32 v[28:29], v[32:33], v[140:141], v[28:29]
	v_lshlrev_b64 v[32:33], 13, v[88:89]
	v_lshlrev_b32_e32 v30, 16, v91
	v_and_b32_e32 v31, 0xffff0000, v91
	v_lshl_add_u64 v[32:33], s[6:7], 0, v[32:33]
	v_pk_fma_f32 v[30:31], v[34:35], v[142:143], v[30:31]
	v_lshl_add_u64 v[32:33], v[32:33], 0, v[156:157]
	flat_store_dwordx4 v[32:33], v[28:31] nt
	s_nop 1
	v_lshlrev_b32_e32 v28, 16, v92
	v_and_b32_e32 v29, 0xffff0000, v92
	v_lshlrev_b32_e32 v30, 16, v93
	v_and_b32_e32 v31, 0xffff0000, v93
	v_pk_fma_f32 v[26:27], v[26:27], v[138:139], v[30:31]
	v_pk_fma_f32 v[24:25], v[24:25], v[136:137], v[28:29]
	flat_store_dwordx4 v[32:33], v[24:27] offset:64 nt
	s_nop 1
	v_lshlrev_b32_e32 v24, 16, v94
	v_and_b32_e32 v25, 0xffff0000, v94
	v_lshlrev_b32_e32 v26, 16, v95
	v_and_b32_e32 v27, 0xffff0000, v95
	v_pk_fma_f32 v[22:23], v[22:23], v[134:135], v[26:27]
	v_pk_fma_f32 v[20:21], v[20:21], v[132:133], v[24:25]
	flat_store_dwordx4 v[32:33], v[20:23] offset:512 nt
	s_nop 1
	v_lshlrev_b32_e32 v20, 16, v96
	v_and_b32_e32 v21, 0xffff0000, v96
	v_lshlrev_b32_e32 v22, 16, v97
	v_and_b32_e32 v23, 0xffff0000, v97
	v_pk_fma_f32 v[14:15], v[14:15], v[130:131], v[22:23]
	v_pk_fma_f32 v[12:13], v[12:13], v[128:129], v[20:21]
	flat_store_dwordx4 v[32:33], v[12:15] offset:576 nt
	s_nop 1
	v_lshlrev_b32_e32 v12, 16, v100
	v_and_b32_e32 v13, 0xffff0000, v100
	v_pk_fma_f32 v[12:13], v[16:17], v[140:141], v[12:13]
	v_lshlrev_b64 v[16:17], 13, v[98:99]
	v_lshlrev_b32_e32 v14, 16, v101
	v_and_b32_e32 v15, 0xffff0000, v101
	v_lshl_add_u64 v[16:17], s[6:7], 0, v[16:17]
	v_pk_fma_f32 v[14:15], v[18:19], v[142:143], v[14:15]
	v_lshl_add_u64 v[16:17], v[16:17], 0, v[156:157]
	flat_store_dwordx4 v[16:17], v[12:15] nt
	s_nop 1
	v_lshlrev_b32_e32 v12, 16, v102
	v_and_b32_e32 v13, 0xffff0000, v102
	v_lshlrev_b32_e32 v14, 16, v103
	v_and_b32_e32 v15, 0xffff0000, v103
	v_pk_fma_f32 v[10:11], v[10:11], v[138:139], v[14:15]
	v_pk_fma_f32 v[8:9], v[8:9], v[136:137], v[12:13]
	flat_store_dwordx4 v[16:17], v[8:11] offset:64 nt
	s_nop 1
	v_lshlrev_b32_e32 v8, 16, v66
	v_and_b32_e32 v9, 0xffff0000, v66
	v_lshlrev_b32_e32 v10, 16, v67
	v_and_b32_e32 v11, 0xffff0000, v67
	v_pk_fma_f32 v[6:7], v[6:7], v[134:135], v[10:11]
	v_pk_fma_f32 v[4:5], v[4:5], v[132:133], v[8:9]
	flat_store_dwordx4 v[16:17], v[4:7] offset:512 nt
	s_nop 1
	v_lshlrev_b32_e32 v4, 16, v64
	v_and_b32_e32 v5, 0xffff0000, v64
	v_lshlrev_b32_e32 v6, 16, v65
	v_and_b32_e32 v7, 0xffff0000, v65
	v_pk_fma_f32 v[2:3], v[2:3], v[130:131], v[6:7]
	v_pk_fma_f32 v[0:1], v[0:1], v[128:129], v[4:5]
	flat_store_dwordx4 v[16:17], v[0:3] offset:576 nt
	s_cbranch_vccnz .LBB0_1077
	s_andn2_b64 vcc, exec, s[12:13]
	s_cbranch_vccnz .LBB0_1076
	s_barrier
	s_branch .LBB0_1076
